# mixer-B loop without the 4 augmentation MFMAs per tile: softmax reference fed through SrcC of the first QK MFMA (shared reference, state rescaled at takeover, underflow guard to the exact redo path);
# speedup vs baseline: 1.0222x; 1.0222x over previous
; DI u16 f2bf(float a) { return (u16)(pk2(a, 0.f) & 0xffffu); }
; DI float bf2f(u16 v) { return __uint_as_float(((unsigned)v) << 16); }
; template <int NS>
; DI void attn_item(const Params& p, int layer, char* smem, VBC& vc, int b, int hq, int qblk) {
;     ...
;                 float mnew = fmaxf(mrun[m], tmax * cexp);
;                 if (fast) mnew = bf2f(f2bf(mnew));
;                 const float alpha = __builtin_amdgcn_exp2f(mrun[m] - mnew);
;                 mrun[m] = mnew;
;                 f32x2 ls2 = {0.f, 0.f};
;                 const f32x2 cc2 = {cexp, cexp}, mm2 = {-mnew, -mnew};
;     #pragma unroll
;                 for (int kt2 = 0; kt2 < 2; ++kt2)
;     #pragma unroll
;                     for (int e = 0; e < 16; e += 2) {
;                         f32x2 sv = {s[kt2][e], s[kt2][e + 1]};
;                         sv = __builtin_elementwise_fma(sv, cc2, mm2);
;                         f32x2 pv = {__builtin_amdgcn_exp2f(sv.x), __builtin_amdgcn_exp2f(sv.y)};
;                         s[kt2][e] = pv.x; s[kt2][e + 1] = pv.y; ls2 += pv;
;                     }
;                 lrun[m] = lrun[m] * alpha + (ls2.x + ls2.y);
;                 if (__any(alpha != 1.f)) {
;     #pragma unroll
;                     for (int t = 0; t < 2; ++t)
;     #pragma unroll
;                         for (int e = 0; e < 16; ++e) O[m][t][e] *= alpha;
;                 }
.Lr_takeover:
	v_readlane_b32 s0, v252, 21
	s_lshr_b32 s0, s0, 4
	s_add_i32 s0, s0, s33
	s_add_i32 s16, s0, 0x10000
	v_lshl_add_u32 v5, v241, 1, s33
	v_lshl_add_u32 v6, v243, 1, s33
	s_nop 0
	v_readfirstlane_b32 s98, v5
	v_readfirstlane_b32 s99, v6
	s_mov_b32 s47, 2
	s_mov_b32 s55, 0x8000
	s_cmp_lt_u32 s47, s21
	s_cselect_b64 s[0:1], -1, 0
	s_sub_i32 s17, s47, s21
	s_min_u32 s17, s47, s17
	s_and_b64 s[0:1], s[0:1], exec
	s_cselect_b32 s0, s20, s27
	s_cselect_b32 s1, s25, s41
	s_cselect_b32 s48, s24, s40
	s_lshl_b32 s49, s17, 6
	s_add_i32 s49, s49, s0
	s_lshl_b32 s0, s17, 7
	s_add_u32 s0, s48, s0
	s_addc_u32 s1, s1, 0
	s_mul_hi_i32 s17, s49, 0x1a80
	s_mulk_i32 s49, 0x1a80
	s_add_u32 s48, s42, s49
	s_addc_u32 s49, s43, s17
	v_add_u32_e32 v2, v206, v222
	s_add_i32 m0, s98, s55
	v_add_u32_e32 v3, v208, v222
	global_load_lds_dwordx4 v2, s[48:49]
	s_add_i32 m0, m0, 0x2000
	v_add_u32_e32 v5, v210, v224
	global_load_lds_dwordx4 v3, s[0:1]
	s_add_i32 m0, s99, s55
	v_add_u32_e32 v6, v212, v224
	global_load_lds_dwordx4 v5, s[48:49]
	s_add_i32 m0, m0, 0x2000
	s_nop 0
	global_load_lds_dwordx4 v6, s[0:1]
	s_mov_b32 s47, 3
	s_mov_b32 s55, 0xc000
	s_cmp_lt_u32 s47, s21
	s_cselect_b64 s[0:1], -1, 0
	s_sub_i32 s17, s47, s21
	s_min_u32 s17, s47, s17
	s_and_b64 s[0:1], s[0:1], exec
	s_cselect_b32 s0, s20, s27
	s_cselect_b32 s1, s25, s41
	s_cselect_b32 s48, s24, s40
	s_lshl_b32 s49, s17, 6
	s_add_i32 s49, s49, s0
	s_lshl_b32 s0, s17, 7
	s_add_u32 s0, s48, s0
	s_addc_u32 s1, s1, 0
	s_mul_hi_i32 s17, s49, 0x1a80
	s_mulk_i32 s49, 0x1a80
	s_add_u32 s48, s42, s49
	s_addc_u32 s49, s43, s17
	v_add_u32_e32 v2, v206, v222
	s_add_i32 m0, s98, s55
	v_add_u32_e32 v3, v208, v222
	global_load_lds_dwordx4 v2, s[48:49]
	s_add_i32 m0, m0, 0x2000
	v_add_u32_e32 v5, v210, v224
	global_load_lds_dwordx4 v3, s[0:1]
	s_add_i32 m0, s99, s55
	v_add_u32_e32 v6, v212, v224
	global_load_lds_dwordx4 v5, s[48:49]
	s_add_i32 m0, m0, 0x2000
	s_nop 0
	global_load_lds_dwordx4 v6, s[0:1]
	v_max_f32_e32 v226, v7, v249
	v_sub_f32_e32 v2, v7, v226
	v_sub_f32_e32 v3, v249, v226
	v_exp_f32_e32 v2, v2
	v_exp_f32_e32 v3, v3
	v_xor_b32_e32 v128, 0x80000000, v226
	v_xor_b32_e32 v129, 0x80000000, v226
	v_xor_b32_e32 v130, 0x80000000, v226
	v_xor_b32_e32 v131, 0x80000000, v226
	v_xor_b32_e32 v132, 0x80000000, v226
	v_xor_b32_e32 v133, 0x80000000, v226
	v_xor_b32_e32 v134, 0x80000000, v226
	v_xor_b32_e32 v135, 0x80000000, v226
	v_xor_b32_e32 v136, 0x80000000, v226
	v_xor_b32_e32 v137, 0x80000000, v226
	v_xor_b32_e32 v138, 0x80000000, v226
	v_xor_b32_e32 v139, 0x80000000, v226
	v_xor_b32_e32 v140, 0x80000000, v226
	v_xor_b32_e32 v141, 0x80000000, v226
	v_xor_b32_e32 v142, 0x80000000, v226
	v_xor_b32_e32 v143, 0x80000000, v226
	v_mul_f32_e32 v194, v194, v2
	v_mul_f32_e32 v4, v4, v3
	v_mul_f32_e32 v64, v64, v2
	v_mul_f32_e32 v65, v65, v2
	v_mul_f32_e32 v66, v66, v2
	v_mul_f32_e32 v67, v67, v2
	v_mul_f32_e32 v68, v68, v2
	v_mul_f32_e32 v69, v69, v2
	v_mul_f32_e32 v70, v70, v2
	v_mul_f32_e32 v71, v71, v2
	v_mul_f32_e32 v72, v72, v2
	v_mul_f32_e32 v73, v73, v2
	v_mul_f32_e32 v74, v74, v2
	v_mul_f32_e32 v75, v75, v2
	v_mul_f32_e32 v76, v76, v2
	v_mul_f32_e32 v77, v77, v2
	v_mul_f32_e32 v78, v78, v2
	v_mul_f32_e32 v79, v79, v2
	v_mul_f32_e32 v32, v32, v2
	v_mul_f32_e32 v33, v33, v2
	v_mul_f32_e32 v34, v34, v2
	v_mul_f32_e32 v35, v35, v2
	v_mul_f32_e32 v36, v36, v2
	v_mul_f32_e32 v37, v37, v2
	v_mul_f32_e32 v38, v38, v2
	v_mul_f32_e32 v39, v39, v2
	v_mul_f32_e32 v40, v40, v2
	v_mul_f32_e32 v41, v41, v2
	v_mul_f32_e32 v42, v42, v2
	v_mul_f32_e32 v43, v43, v2
	v_mul_f32_e32 v44, v44, v2
	v_mul_f32_e32 v45, v45, v2
	v_mul_f32_e32 v46, v46, v2
	v_mul_f32_e32 v47, v47, v2
	v_mul_f32_e32 v48, v48, v3
	v_mul_f32_e32 v49, v49, v3
	v_mul_f32_e32 v50, v50, v3
	v_mul_f32_e32 v51, v51, v3
	v_mul_f32_e32 v52, v52, v3
	v_mul_f32_e32 v53, v53, v3
	v_mul_f32_e32 v54, v54, v3
	v_mul_f32_e32 v55, v55, v3
	v_mul_f32_e32 v56, v56, v3
	v_mul_f32_e32 v57, v57, v3
	v_mul_f32_e32 v58, v58, v3
	v_mul_f32_e32 v59, v59, v3
	v_mul_f32_e32 v60, v60, v3
	v_mul_f32_e32 v61, v61, v3
	v_mul_f32_e32 v62, v62, v3
	v_mul_f32_e32 v63, v63, v3
	v_mul_f32_e32 v16, v16, v3
	v_mul_f32_e32 v17, v17, v3
	v_mul_f32_e32 v18, v18, v3
	v_mul_f32_e32 v19, v19, v3
	v_mul_f32_e32 v20, v20, v3
	v_mul_f32_e32 v21, v21, v3
	v_mul_f32_e32 v22, v22, v3
	v_mul_f32_e32 v23, v23, v3
	v_mul_f32_e32 v24, v24, v3
	v_mul_f32_e32 v25, v25, v3
	v_mul_f32_e32 v26, v26, v3
	v_mul_f32_e32 v27, v27, v3
	v_mul_f32_e32 v28, v28, v3
	v_mul_f32_e32 v29, v29, v3
	v_mul_f32_e32 v30, v30, v3
	v_mul_f32_e32 v31, v31, v3
	v_mov_b32_e32 v7, v226
	v_mov_b32_e32 v249, v226
	s_movk_i32 s17, 0x2000
; template <int NS>
; DI void attn_item(const Params& p, int layer, char* smem, VBC& vc, int b, int hq, int qblk) {
;     ...
;         auto qk = [&](const int m, f32x16 (&s)[2]) {
; #pragma unroll
;             for (int kt2 = 0; kt2 < 2; ++kt2)
; #pragma unroll
;                 for (int e = 0; e < 16; ++e) s[kt2][e] = 0.f;
;             __builtin_amdgcn_s_setprio(1);
; #pragma unroll
;             for (int ks = 0; ks < NKS; ++ks)
; #pragma unroll
;                 for (int kt2 = 0; kt2 < 2; ++kt2) s[kt2] = MFMA(ld8(cK + (kt2 * 32 + r) * 64 + (((m * DQK + ks * 16)) ^ hs16)), qf[m][ks], s[kt2]);
; #pragma unroll
;             for (int kt2 = 0; kt2 < 2; ++kt2) { uint4 qa4 = {qaug[m], 0u, 0u, 0u}; s[kt2] = MFMA(kones, __builtin_bit_cast(bf16x8, qa4), s[kt2]); }
;             __builtin_amdgcn_s_setprio(0);
;     ...
;             if (fixed) {
;                 float ls = 0.f;
; #pragma unroll
;                 for (int kt2 = 0; kt2 < 2; ++kt2)
; #pragma unroll
;                     for (int e = 0; e < 16; ++e) { const float pv = __builtin_amdgcn_exp2f(s[kt2][e]); s[kt2][e] = pv; ls += pv; }
;                 lrun[m] += ls;
;             } else {
;                 float tmax = -1e30f;
;     #pragma unroll
;                 for (int kt2 = 0; kt2 < 2; ++kt2)
;     #pragma unroll
;                     for (int e = 0; e < 16; ++e) tmax = fmaxf(tmax, s[kt2][e]);
;                 tmax = fmaxf(tmax, __shfl_xor(tmax, 32));
;                 float mnew = fmaxf(mrun[m], tmax * cexp);
;                 if (fast) mnew = bf2f(f2bf(mnew));
;                 const float alpha = __builtin_amdgcn_exp2f(mrun[m] - mnew);
;                 mrun[m] = mnew;
;                 f32x2 ls2 = {0.f, 0.f};
;                 const f32x2 cc2 = {cexp, cexp}, mm2 = {-mnew, -mnew};
;     #pragma unroll
;                 for (int kt2 = 0; kt2 < 2; ++kt2)
;     #pragma unroll
;                     for (int e = 0; e < 16; e += 2) {
;                         f32x2 sv = {s[kt2][e], s[kt2][e + 1]};
;                         sv = __builtin_elementwise_fma(sv, cc2, mm2);
;                         f32x2 pv = {__builtin_amdgcn_exp2f(sv.x), __builtin_amdgcn_exp2f(sv.y)};
;                         s[kt2][e] = pv.x; s[kt2][e + 1] = pv.y; ls2 += pv;
;                     }
;                 lrun[m] = lrun[m] * alpha + (ls2.x + ls2.y);
;                 if (__any(alpha != 1.f)) {
;     #pragma unroll
.Lr_body:
	v_lshl_add_u32 v226, s17, 1, v248
	v_lshl_add_u32 v5, v201, 1, v226
	v_lshl_add_u32 v6, v245, 1, v226
	ds_read_b128 v[112:115], v5
	ds_read_b128 v[116:119], v5 offset:4096
	ds_read_b128 v[120:123], v6
	ds_read_b128 v[124:127], v6 offset:4096
	v_lshl_add_u32 v223, v246, 1, v226
	v_lshl_add_u32 v225, v247, 1, v226
	s_waitcnt lgkmcnt(3)
	v_mfma_f32_32x32x16_bf16 v[96:111], v[112:115], v[176:179], v[128:143]
	s_waitcnt lgkmcnt(2)
	v_mfma_f32_32x32x16_bf16 v[80:95], v[116:119], v[176:179], v[128:143]
	s_waitcnt lgkmcnt(1)
	v_mfma_f32_32x32x16_bf16 v[96:111], v[120:123], v[180:183], v[96:111]
	s_waitcnt lgkmcnt(0)
	v_mfma_f32_32x32x16_bf16 v[80:95], v[124:127], v[180:183], v[80:95]
	ds_read_b128 v[112:115], v223
	ds_read_b128 v[116:119], v223 offset:4096
	ds_read_b128 v[120:123], v225
	ds_read_b128 v[124:127], v225 offset:4096
	s_waitcnt lgkmcnt(3)
	v_mfma_f32_32x32x16_bf16 v[144:159], v[112:115], v[184:187], v[128:143]
	s_waitcnt lgkmcnt(2)
	v_mfma_f32_32x32x16_bf16 v[160:175], v[116:119], v[184:187], v[128:143]
	s_waitcnt lgkmcnt(1)
	v_mfma_f32_32x32x16_bf16 v[144:159], v[120:123], v[188:191], v[144:159]
	s_waitcnt lgkmcnt(0)
	v_mfma_f32_32x32x16_bf16 v[160:175], v[124:127], v[188:191], v[160:175]
	ds_read_b128 v[112:115], v5 offset:8192
	ds_read_b128 v[116:119], v5 offset:12288
	ds_read_b128 v[120:123], v6 offset:8192
	ds_read_b128 v[124:127], v6 offset:12288
	v_exp_f32_e32 v96, v96
	v_exp_f32_e32 v97, v97
	v_exp_f32_e32 v98, v98
	v_exp_f32_e32 v99, v99
	v_exp_f32_e32 v100, v100
	v_exp_f32_e32 v101, v101
	v_pk_add_f32 v[2:3], v[96:97], v[98:99]
	v_exp_f32_e32 v102, v102
	v_exp_f32_e32 v103, v103
	v_pk_add_f32 v[2:3], v[2:3], v[100:101]
	v_exp_f32_e32 v104, v104
	v_exp_f32_e32 v105, v105
	v_pk_add_f32 v[2:3], v[2:3], v[102:103]
	v_exp_f32_e32 v106, v106
	v_exp_f32_e32 v107, v107
	v_pk_add_f32 v[2:3], v[2:3], v[104:105]
	v_exp_f32_e32 v108, v108
	v_exp_f32_e32 v109, v109
	v_pk_add_f32 v[2:3], v[2:3], v[106:107]
	v_exp_f32_e32 v110, v110
	v_exp_f32_e32 v111, v111
	v_pk_add_f32 v[2:3], v[2:3], v[108:109]
	v_exp_f32_e32 v80, v80
	v_exp_f32_e32 v81, v81
	v_pk_add_f32 v[2:3], v[2:3], v[110:111]
	v_exp_f32_e32 v82, v82
	v_exp_f32_e32 v83, v83
	v_pk_add_f32 v[2:3], v[2:3], v[80:81]
	v_exp_f32_e32 v84, v84
	v_exp_f32_e32 v85, v85
	v_pk_add_f32 v[2:3], v[2:3], v[82:83]
	v_exp_f32_e32 v86, v86
	v_exp_f32_e32 v87, v87
	v_pk_add_f32 v[2:3], v[2:3], v[84:85]
	v_exp_f32_e32 v88, v88
	v_exp_f32_e32 v89, v89
	v_pk_add_f32 v[2:3], v[2:3], v[86:87]
	v_exp_f32_e32 v90, v90
	v_exp_f32_e32 v91, v91
	v_pk_add_f32 v[2:3], v[2:3], v[88:89]
	v_exp_f32_e32 v92, v92
	v_exp_f32_e32 v93, v93
	v_pk_add_f32 v[2:3], v[2:3], v[90:91]
	v_exp_f32_e32 v94, v94
	v_exp_f32_e32 v95, v95
	v_pk_add_f32 v[2:3], v[2:3], v[92:93]
	v_mov_b32_e32 v96, v96
	v_pk_add_f32 v[2:3], v[2:3], v[94:95]
	v_cvt_pk_bf16_f32 v96, v96, v97
	v_cvt_pk_bf16_f32 v97, v98, v99
	v_cvt_pk_bf16_f32 v98, v100, v101
	v_cvt_pk_bf16_f32 v99, v102, v103
	v_cvt_pk_bf16_f32 v100, v104, v105
	v_cvt_pk_bf16_f32 v101, v106, v107
	v_cvt_pk_bf16_f32 v102, v108, v109
	v_cvt_pk_bf16_f32 v103, v110, v111
	v_cvt_pk_bf16_f32 v80, v80, v81
	v_cvt_pk_bf16_f32 v81, v82, v83
	v_cvt_pk_bf16_f32 v82, v84, v85
	v_cvt_pk_bf16_f32 v83, v86, v87
	v_cvt_pk_bf16_f32 v84, v88, v89
	v_cvt_pk_bf16_f32 v85, v90, v91
	v_cvt_pk_bf16_f32 v86, v92, v93
	v_cvt_pk_bf16_f32 v87, v94, v95
	v_add_f32_e32 v2, v2, v3
	v_add_f32_e32 v194, v194, v2
	ds_read_b128 v[104:107], v223 offset:8192
	ds_read_b128 v[108:111], v223 offset:12288
	ds_read_b128 v[88:91], v225 offset:8192
	ds_read_b128 v[92:95], v225 offset:12288
	s_waitcnt lgkmcnt(7)
	v_mfma_f32_32x32x16_bf16 v[64:79], v[112:115], v[96:99], v[64:79]
	v_exp_f32_e32 v144, v144
	v_exp_f32_e32 v145, v145
	v_exp_f32_e32 v146, v146
	v_exp_f32_e32 v147, v147
	v_exp_f32_e32 v148, v148
	v_exp_f32_e32 v149, v149
	v_pk_add_f32 v[14:15], v[144:145], v[146:147]
	v_exp_f32_e32 v150, v150
	s_waitcnt lgkmcnt(6)
	v_mfma_f32_32x32x16_bf16 v[32:47], v[116:119], v[96:99], v[32:47]
	v_exp_f32_e32 v151, v151
	v_pk_add_f32 v[14:15], v[14:15], v[148:149]
	v_exp_f32_e32 v152, v152
	v_exp_f32_e32 v153, v153
	v_pk_add_f32 v[14:15], v[14:15], v[150:151]
	v_exp_f32_e32 v154, v154
	v_exp_f32_e32 v155, v155
	v_pk_add_f32 v[14:15], v[14:15], v[152:153]
	s_waitcnt lgkmcnt(5)
	v_mfma_f32_32x32x16_bf16 v[64:79], v[120:123], v[100:103], v[64:79]
	v_exp_f32_e32 v156, v156
	v_exp_f32_e32 v157, v157
	v_pk_add_f32 v[14:15], v[14:15], v[154:155]
	v_exp_f32_e32 v158, v158
	v_exp_f32_e32 v159, v159
	v_pk_add_f32 v[14:15], v[14:15], v[156:157]
	v_exp_f32_e32 v160, v160
	v_exp_f32_e32 v161, v161
	s_waitcnt lgkmcnt(4)
	v_mfma_f32_32x32x16_bf16 v[32:47], v[124:127], v[100:103], v[32:47]
	v_pk_add_f32 v[14:15], v[14:15], v[158:159]
	v_exp_f32_e32 v162, v162
	v_exp_f32_e32 v163, v163
	v_pk_add_f32 v[14:15], v[14:15], v[160:161]
	v_exp_f32_e32 v164, v164
	v_exp_f32_e32 v165, v165
	v_pk_add_f32 v[14:15], v[14:15], v[162:163]
	v_exp_f32_e32 v166, v166
	s_waitcnt lgkmcnt(3)
	v_mfma_f32_32x32x16_bf16 v[64:79], v[104:107], v[80:83], v[64:79]
	v_exp_f32_e32 v167, v167
	v_pk_add_f32 v[14:15], v[14:15], v[164:165]
	v_exp_f32_e32 v168, v168
	v_exp_f32_e32 v169, v169
	v_pk_add_f32 v[14:15], v[14:15], v[166:167]
	v_exp_f32_e32 v170, v170
	v_exp_f32_e32 v171, v171
	v_pk_add_f32 v[14:15], v[14:15], v[168:169]
	s_waitcnt lgkmcnt(2)
	v_mfma_f32_32x32x16_bf16 v[32:47], v[108:111], v[80:83], v[32:47]
	v_exp_f32_e32 v172, v172
	v_exp_f32_e32 v173, v173
	v_pk_add_f32 v[14:15], v[14:15], v[170:171]
	v_exp_f32_e32 v174, v174
	v_exp_f32_e32 v175, v175
	v_pk_add_f32 v[14:15], v[14:15], v[172:173]
	v_mov_b32_e32 v144, v144
	v_pk_add_f32 v[14:15], v[14:15], v[174:175]
	s_waitcnt lgkmcnt(1)
	v_mfma_f32_32x32x16_bf16 v[64:79], v[88:91], v[84:87], v[64:79]
	s_waitcnt lgkmcnt(0)
	v_mfma_f32_32x32x16_bf16 v[32:47], v[92:95], v[84:87], v[32:47]
	v_cvt_pk_bf16_f32 v144, v144, v145
	v_cvt_pk_bf16_f32 v145, v146, v147
	v_cvt_pk_bf16_f32 v146, v148, v149
	v_cvt_pk_bf16_f32 v147, v150, v151
	v_cvt_pk_bf16_f32 v148, v152, v153
	v_cvt_pk_bf16_f32 v149, v154, v155
	v_cvt_pk_bf16_f32 v150, v156, v157
	v_cvt_pk_bf16_f32 v151, v158, v159
	v_cvt_pk_bf16_f32 v160, v160, v161
	v_cvt_pk_bf16_f32 v161, v162, v163
	v_cvt_pk_bf16_f32 v162, v164, v165
	v_cvt_pk_bf16_f32 v163, v166, v167
	v_cvt_pk_bf16_f32 v164, v168, v169
	v_cvt_pk_bf16_f32 v165, v170, v171
	v_cvt_pk_bf16_f32 v166, v172, v173
	v_cvt_pk_bf16_f32 v167, v174, v175
	v_add_f32_e32 v14, v14, v15
	v_add_f32_e32 v4, v4, v14
	s_nop 1
	s_cmp_lg_u32 s46, s44
	s_cbranch_scc0 .Lr_last
; #define MFMA(a, b, c) __builtin_amdgcn_mfma_f32_32x32x16_bf16((a), (b), (c), 0, 0, 0)
; #define VSYNC() vb_sync(vc)
; template <int NS>
; DI void attn_item(const Params& p, int layer, char* smem, VBC& vc, int b, int hq, int qblk) {
;     ...
;     auto tile_ptrs = [&](int it, const u16*& kp, const u16*& vp) {
;         if (it < lat1 - lat0) { int kt = lat0 + it; kp = P + (size_t)(b * SEQ + kt * 64) * PC + kcol; vp = VT + kt * 64; }
;         else { int c = it - (lat1 - lat0); kp = P + (size_t)(NLAT + b * CTXL + c * 64) * PC + kcol; vp = VT + SEQ + c * 64; }
;     };
;     auto dma_tile = [&](int it, int st) {
;         const u16 *kp, *vp; tile_ptrs(it, kp, vp);
; #pragma unroll
;         for (int i = 0; i < 2; ++i) {
;             const int row = wave4 * 16 + i * 8 + drow;
;             const int chunk = dslot ^ ((row >> 1) & 7);
;             lds_u32* dk = (lds_u32*)(sK + st * 8192 + (wave4 * 16 + i * 8) * 64);
;             lds_u32* dv = (lds_u32*)(sK + st * 8192 + 4096 + (wave4 * 16 + i * 8) * 64);
;             __builtin_amdgcn_global_load_lds((const unsigned*)(kp + (size_t)row * PC + chunk * 8), dk, 16, 0, 0);
;             __builtin_amdgcn_global_load_lds((const unsigned*)(vp + (size_t)row * KVS + chunk * 8), dv, 16, 0, 0);
;         }
;     };
;     const int hs16 = ((h ^ ((r >> 1) & 7)) << 3);
;     const bf16x8 kones = __builtin_bit_cast(bf16x8, (uint4){0x00003F80u, 0u, 0u, 0u});
;     auto run_tiles = [&](const bool fast) {
;     dma_tile(0, 0);
;     asm volatile("s_waitcnt vmcnt(0)" ::: "memory");
;     VSYNC();
;     for (int it = 0; it < ntiles; ++it) {
;         const int buf = it & 1;
;         if (it + 1 < ntiles) dma_tile(it + 1, buf ^ 1);
;     ...
;         auto pvm = [&](const int m, const bf16x8 (&pf)[2][2]) {
;             __builtin_amdgcn_s_setprio(1);
; #pragma unroll
;             for (int kk = 0; kk < 4; ++kk)
; #pragma unroll
;                 for (int dvt = 0; dvt < 2; ++dvt) O[m][dvt] = MFMA(ld8(cV + (dvt * 32 + r) * 64 + ((kk * 16) ^ hs16)), pf[kk >> 1][kk & 1], O[m][dvt]);
;             __builtin_amdgcn_s_setprio(0);
;         };
	v_mfma_f32_32x32x16_bf16 v[48:63], v[112:115], v[144:147], v[48:63]
	s_waitcnt vmcnt(0)
	v_mov_b32_e32 v2, s16
	v_mov_b32_e32 v3, s46
	s_mov_b64 exec, 1
	ds_write_b32 v2, v3
	s_mov_b64 exec, -1
	s_add_i32 s0, s33, 0x10000
	v_mov_b32_e32 v6, s0
	ds_read_b128 v[8:11], v6
	v_mfma_f32_32x32x16_bf16 v[16:31], v[116:119], v[144:147], v[16:31]
	s_add_i32 s54, s46, -1
	s_max_i32 s54, s54, 1
	s_add_i32 s47, s46, 3
	s_and_b32 s55, s47, 3
	s_lshl_b32 s55, s55, 14
	s_cmp_lt_u32 s47, s21
	s_cselect_b64 s[0:1], -1, 0
	s_sub_i32 s17, s47, s21
	s_min_u32 s17, s47, s17
	s_and_b64 s[0:1], s[0:1], exec
	s_cselect_b32 s0, s20, s27
	s_cselect_b32 s1, s25, s41
	s_cselect_b32 s48, s24, s40
	s_lshl_b32 s49, s17, 6
	s_add_i32 s49, s49, s0
	s_lshl_b32 s0, s17, 7
	s_add_u32 s0, s48, s0
	s_addc_u32 s1, s1, 0
	s_mul_hi_i32 s17, s49, 0x1a80
	s_mulk_i32 s49, 0x1a80
	s_add_u32 s48, s42, s49
	s_addc_u32 s49, s43, s17
	v_mfma_f32_32x32x16_bf16 v[48:63], v[120:123], v[148:151], v[48:63]
	v_add_u32_e32 v2, v206, v222
	v_add_u32_e32 v3, v208, v222
	v_add_u32_e32 v5, v210, v224
	s_waitcnt lgkmcnt(0)
	v_min3_u32 v8, v8, v9, v10
	v_min_u32_e32 v8, v8, v11
	v_mfma_f32_32x32x16_bf16 v[16:31], v[124:127], v[148:151], v[16:31]
	v_cmp_gt_u32_e32 vcc, s54, v8
	s_cbranch_vccnz .Lr_pollslow
.Lr_ready:
	s_cmp_lt_u32 s47, s26
	s_cbranch_scc0 .Lr_nodma
	s_add_i32 m0, s98, s55
	v_add_u32_e32 v6, v212, v224
	global_load_lds_dwordx4 v2, s[48:49]
	v_mfma_f32_32x32x16_bf16 v[48:63], v[104:107], v[160:163], v[48:63]
	s_add_i32 m0, m0, 0x2000
	s_nop 0
	global_load_lds_dwordx4 v3, s[0:1]
	v_mfma_f32_32x32x16_bf16 v[16:31], v[108:111], v[160:163], v[16:31]
	s_add_i32 m0, s99, s55
	s_nop 0
	global_load_lds_dwordx4 v5, s[48:49]
	v_mfma_f32_32x32x16_bf16 v[48:63], v[88:91], v[164:167], v[48:63]
	s_add_i32 m0, m0, 0x2000
	s_nop 0
	global_load_lds_dwordx4 v6, s[0:1]
	v_mfma_f32_32x32x16_bf16 v[16:31], v[92:95], v[164:167], v[16:31]
	s_branch .Lr_next
.Lr_nodma:
	v_mfma_f32_32x32x16_bf16 v[48:63], v[104:107], v[160:163], v[48:63]
	v_mfma_f32_32x32x16_bf16 v[16:31], v[108:111], v[160:163], v[16:31]
	v_mfma_f32_32x32x16_bf16 v[48:63], v[88:91], v[164:167], v[48:63]
	v_mfma_f32_32x32x16_bf16 v[16:31], v[92:95], v[164:167], v[16:31]

; #define MFMA(a, b, c) __builtin_amdgcn_mfma_f32_32x32x16_bf16((a), (b), (c), 0, 0, 0)
; template <int NS>
; DI void attn_item(const Params& p, int layer, char* smem, VBC& vc, int b, int hq, int qblk) {
;     ...
;         auto pvm = [&](const int m, const bf16x8 (&pf)[2][2]) {
;             __builtin_amdgcn_s_setprio(1);
; #pragma unroll
;             for (int kk = 0; kk < 4; ++kk)
; #pragma unroll
;                 for (int dvt = 0; dvt < 2; ++dvt) O[m][dvt] = MFMA(ld8(cV + (dvt * 32 + r) * 64 + ((kk * 16) ^ hs16)), pf[kk >> 1][kk & 1], O[m][dvt]);
;             __builtin_amdgcn_s_setprio(0);
;         };
;     ...
;     for (int attempt = 0; attempt < 2; ++attempt) {
;         if (attempt) init_state();
;         run_tiles(attempt == 0);
;         bool bad = !(lrun[0] < 1e37f);
;         if (NS == 2) bad = bad || !(lrun[NS - 1] < 1e37f);
.Lr_last:
	v_mfma_f32_32x32x16_bf16 v[48:63], v[112:115], v[144:147], v[48:63]
	v_mfma_f32_32x32x16_bf16 v[16:31], v[116:119], v[144:147], v[16:31]
	v_mfma_f32_32x32x16_bf16 v[48:63], v[120:123], v[148:151], v[48:63]
	v_mfma_f32_32x32x16_bf16 v[16:31], v[124:127], v[148:151], v[16:31]
	v_mfma_f32_32x32x16_bf16 v[48:63], v[104:107], v[160:163], v[48:63]
	v_mfma_f32_32x32x16_bf16 v[16:31], v[108:111], v[160:163], v[16:31]
	v_mfma_f32_32x32x16_bf16 v[48:63], v[88:91], v[164:167], v[48:63]
	v_mfma_f32_32x32x16_bf16 v[16:31], v[92:95], v[164:167], v[16:31]
	s_mov_b32 s0, 0x0da24260
	v_mov_b32_e32 v2, 0x7f800000
	v_cmp_gt_f32_e32 vcc, s0, v194
	s_nop 1
	v_cndmask_b32_e32 v223, v194, v2, vcc
	v_cmp_gt_f32_e32 vcc, s0, v4
	s_nop 1
	v_cndmask_b32_e32 v193, v4, v2, vcc
	v_mov_b32_e32 v226, v7
	v_mov_b32_e32 v3, v0
	v_mov_b32_e32 v0, v249
	v_mov_b32_e32 v195, v192
	s_waitcnt vmcnt(0)
	s_add_i32 s45, s45, -4
	s_branch .LBB0_964
